# final norm: row loop pipelined one row deep (next row's six loads requested before the current row is normalised and stored)
# baseline (speedup 1.0000x reference)
.LBB0_1760:
	s_cmp_lt_i32 s92, 13
	s_cselect_b64 s[0:1], -1, 0
	s_cmp_gt_i32 s93, 12
	s_cselect_b64 s[2:3], -1, 0
	s_and_b64 s[0:1], s[0:1], s[2:3]
	s_andn2_b64 vcc, exec, s[0:1]
	s_cbranch_vccnz .LBB0_1764
	s_lshl_b32 s0, s90, 3
	s_add_i32 s0, s0, s33
	s_cmpk_gt_i32 s0, 0x41ff
	s_cbranch_scc1 .LBB0_1764
	v_readlane_b32 s4, v254, 25
	v_lshlrev_b32_e32 v16, 5, v174
	v_readlane_b32 s18, v254, 39
	v_readlane_b32 s19, v254, 40
	s_waitcnt lgkmcnt(0)
	s_nop 3
	global_load_dwordx4 v[0:3], v16, s[18:19] offset:16
	global_load_dwordx4 v[4:7], v16, s[18:19]
	global_load_dwordx4 v[8:11], v16, s[18:19] offset:2064
	global_load_dwordx4 v[12:15], v16, s[18:19] offset:2048
	v_readlane_b32 s5, v254, 26
	s_lshl_b32 s2, s88, 3
	s_ashr_i32 s1, s0, 31
	v_readlane_b32 s6, v254, 27
	v_readlane_b32 s7, v254, 28
	v_readlane_b32 s8, v254, 29
	v_readlane_b32 s9, v254, 30
	v_readlane_b32 s10, v254, 31
	v_readlane_b32 s11, v254, 32
	s_lshl_b64 s[4:5], s[0:1], 11
	s_ashr_i32 s3, s2, 31
	v_lshl_or_b32 v18, v174, 4, s4
	v_mov_b32_e32 v19, s5
	s_lshl_b64 s[4:5], s[2:3], 11
	s_lshl_b64 s[6:7], s[0:1], 6
	s_lshl_b64 s[8:9], s[2:3], 6
	s_lshl_b64 s[10:11], s[0:1], 12
	s_add_u32 s10, s84, s10
	v_mov_b32_e32 v17, 0
	s_addc_u32 s11, s85, s11
	v_lshl_add_u64 v[20:21], s[10:11], 0, v[16:17]
	s_mov_b64 s[10:11], 0x810
	v_readlane_b32 s14, v254, 35
	v_readlane_b32 s15, v254, 36
	v_lshl_add_u64 v[20:21], v[20:21], 0, s[10:11]
	s_lshl_b64 s[10:11], s[2:3], 12
	v_mov_b32_e32 v16, 0xb00000
	v_mov_b32_e32 v22, 0x358637bd
	s_mov_b32 s1, 0x13800000
	v_readlane_b32 s12, v254, 33
	v_readlane_b32 s13, v254, 34
	v_readlane_b32 s16, v254, 37
	v_readlane_b32 s17, v254, 38
	s_mov_b64 s[14:15], s[18:19]
	s_waitcnt vmcnt(0)
	s_add_u32 s12, s86, s6
	v_lshl_add_u64 v[84:85], s[86:87], 0, v[18:19]
	s_addc_u32 s13, s87, s7
	v_add_co_u32_e32 v86, vcc, s1, v84
	s_add_u32 s14, s12, 0xb00000
	s_nop 0
	v_addc_co_u32_e32 v87, vcc, 0, v85, vcc
	global_load_dwordx4 v[60:63], v16, s[12:13]
	s_addc_u32 s15, s13, 0
	global_load_dwordx4 v[64:67], v17, s[14:15] offset:48
	global_load_dwordx4 v[68:71], v17, s[14:15] offset:32
	global_load_dwordx4 v[72:75], v17, s[14:15] offset:16
	global_load_dwordx4 v[76:79], v[86:87], off nt
	global_load_dwordx4 v[80:83], v[86:87], off offset:1024 nt
	s_add_i32 s0, s0, s2
	s_add_u32 s6, s6, s8
	s_addc_u32 s7, s7, s9
	v_lshl_add_u64 v[18:19], v[18:19], 0, s[4:5]
	s_cmpk_lt_i32 s0, 0x4200
	s_cselect_b32 s98, 1, 0
	s_waitcnt vmcnt(0)
.LBB0_1763:
	s_waitcnt vmcnt(4)
	v_mov_b32_e32 v24, v60
	v_mov_b32_e32 v25, v61
	v_mov_b32_e32 v26, v62
	v_mov_b32_e32 v27, v63
	v_mov_b32_e32 v28, v64
	v_mov_b32_e32 v29, v65
	v_mov_b32_e32 v30, v66
	v_mov_b32_e32 v31, v67
	v_mov_b32_e32 v32, v68
	v_mov_b32_e32 v33, v69
	v_mov_b32_e32 v34, v70
	v_mov_b32_e32 v35, v71
	v_mov_b32_e32 v36, v72
	v_mov_b32_e32 v37, v73
	v_mov_b32_e32 v38, v74
	v_mov_b32_e32 v39, v75
	v_mov_b32_e32 v40, v76
	v_mov_b32_e32 v41, v77
	v_mov_b32_e32 v42, v78
	v_mov_b32_e32 v43, v79
	v_mov_b32_e32 v50, v80
	v_mov_b32_e32 v51, v81
	v_mov_b32_e32 v52, v82
	v_mov_b32_e32 v53, v83
	s_mov_b32 s99, s98
	s_cmp_eq_u32 s98, 1
	s_cbranch_scc0 .Lp12_nonext
	s_add_u32 s12, s86, s6
	v_lshl_add_u64 v[84:85], s[86:87], 0, v[18:19]
	s_addc_u32 s13, s87, s7
	v_add_co_u32_e32 v86, vcc, s1, v84
	s_add_u32 s14, s12, 0xb00000
	s_nop 0
	v_addc_co_u32_e32 v87, vcc, 0, v85, vcc
	global_load_dwordx4 v[60:63], v16, s[12:13]
	s_addc_u32 s15, s13, 0
	global_load_dwordx4 v[64:67], v17, s[14:15] offset:48
	global_load_dwordx4 v[68:71], v17, s[14:15] offset:32
	global_load_dwordx4 v[72:75], v17, s[14:15] offset:16
	global_load_dwordx4 v[76:79], v[86:87], off nt
	global_load_dwordx4 v[80:83], v[86:87], off offset:1024 nt
	s_add_i32 s0, s0, s2
	s_add_u32 s6, s6, s8
	s_addc_u32 s7, s7, s9
	v_lshl_add_u64 v[18:19], v[18:19], 0, s[4:5]
	s_cmpk_lt_i32 s0, 0x4200
	s_cselect_b32 s98, 1, 0
.Lp12_nonext:
	v_mov_b32_e32 v46, v25
	v_mov_b32_e32 v47, v26
	v_mov_b32_e32 v25, v27
	v_pk_add_f32 v[24:25], v[46:47], v[24:25]
	v_add_f32_e32 v32, v32, v33
	v_add_f32_e32 v23, v24, v25
	v_mov_b32_e32 v24, v37
	v_mov_b32_e32 v25, v38
	v_mov_b32_e32 v37, v39
	v_pk_add_f32 v[24:25], v[24:25], v[36:37]
	v_add_f32_e32 v34, v34, v35
	v_pk_add_f32 v[24:25], v[24:25], v[24:25] op_sel:[0,1] op_sel_hi:[1,0]
	v_mov_b32_e32 v39, v28
	v_mov_b32_e32 v33, v30
	v_mov_b32_e32 v35, v31
	v_add_f32_e32 v38, 0, v23
	v_mov_b32_e32 v25, v29
	v_pk_add_f32 v[30:31], v[32:33], v[34:35]
	v_pk_add_f32 v[24:25], v[38:39], v[24:25]
	v_lshlrev_b32_e32 v26, 16, v40
	v_pk_add_f32 v[24:25], v[24:25], v[30:31]
	v_and_b32_e32 v27, 0xffff0000, v40
	v_add_f32_e32 v23, v24, v25
	v_fmamk_f32 v23, v23, 0x3a800000, v22
	v_rsq_f32_e32 v32, v23
	v_lshlrev_b32_e32 v40, 16, v41
	v_and_b32_e32 v41, 0xffff0000, v41
	v_lshlrev_b32_e32 v48, 16, v42
	v_and_b32_e32 v49, 0xffff0000, v42
	v_lshlrev_b32_e32 v42, 16, v43
	v_and_b32_e32 v43, 0xffff0000, v43
	v_pk_mul_f32 v[24:25], v[32:33], v[26:27] op_sel_hi:[0,1]
	v_pk_mul_f32 v[26:27], v[32:33], v[40:41] op_sel_hi:[0,1]
	v_pk_mul_f32 v[28:29], v[32:33], v[48:49] op_sel_hi:[0,1]
	v_pk_mul_f32 v[30:31], v[32:33], v[42:43] op_sel_hi:[0,1]
	v_pk_mul_f32 v[26:27], v[6:7], v[26:27]
	v_pk_mul_f32 v[24:25], v[4:5], v[24:25]
	v_pk_mul_f32 v[30:31], v[2:3], v[30:31]
	v_pk_mul_f32 v[28:29], v[0:1], v[28:29]
	global_store_dwordx4 v[20:21], v[24:27], off offset:-2064 nt
	global_store_dwordx4 v[20:21], v[28:31], off offset:-2048 nt
	s_nop 1
	v_lshlrev_b32_e32 v28, 16, v50
	v_and_b32_e32 v29, 0xffff0000, v50
	v_lshlrev_b32_e32 v24, 16, v51
	v_and_b32_e32 v25, 0xffff0000, v51
	v_lshlrev_b32_e32 v30, 16, v52
	v_and_b32_e32 v31, 0xffff0000, v52
	v_lshlrev_b32_e32 v26, 16, v53
	v_and_b32_e32 v27, 0xffff0000, v53
	v_pk_mul_f32 v[28:29], v[32:33], v[28:29] op_sel_hi:[0,1]
	v_pk_mul_f32 v[24:25], v[32:33], v[24:25] op_sel_hi:[0,1]
	v_pk_mul_f32 v[34:35], v[32:33], v[30:31] op_sel_hi:[0,1]
	v_pk_mul_f32 v[30:31], v[32:33], v[26:27] op_sel_hi:[0,1]
	v_pk_mul_f32 v[26:27], v[14:15], v[24:25]
	v_pk_mul_f32 v[24:25], v[12:13], v[28:29]
	v_pk_mul_f32 v[30:31], v[10:11], v[30:31]
	v_pk_mul_f32 v[28:29], v[8:9], v[34:35]
	global_store_dwordx4 v[20:21], v[24:27], off offset:-16 nt
	global_store_dwordx4 v[20:21], v[28:31], off nt
	v_lshl_add_u64 v[20:21], v[20:21], 0, s[10:11]
	s_cmp_eq_u32 s99, 1
	s_cbranch_scc1 .LBB0_1763
